# SGU position loop hand-unrolled: all gate-row/bias loads issued before the MFMAs, W fragments double-buffered, epilogue of tile n-1 under MFMAs of tile n
# speedup vs baseline: 1.0059x; 1.0059x over previous
.LBB0_250:
	v_mov_b32_e32 v144, v22
	v_ashrrev_i32_e32 v145, 31, v22
	v_lshl_add_u64 v[144:145], v[144:145], 2, s[8:9]
	global_load_dword v80, v[144:145], off
	global_load_dword v81, v[144:145], off offset:64
	global_load_dword v82, v[144:145], off offset:128
	global_load_dword v83, v[144:145], off offset:192
	global_load_dword v84, v[144:145], off offset:256
	global_load_dword v85, v[144:145], off offset:320
	global_load_dword v86, v[144:145], off offset:384
	global_load_dword v87, v[144:145], off offset:448
	s_mov_b32 s98, 0xc200000
	s_mov_b32 s99, 0
	v_lshl_add_u64 v[146:147], v[24:25], 0, s[98:99]
	global_load_dwordx2 v[88:89], v[146:147], off
	v_lshl_add_u64 v[146:147], v[18:19], 0, s[98:99]
	global_load_dwordx2 v[90:91], v[146:147], off
	s_add_u32 s98, s98, 0x10000
	v_lshl_add_u64 v[146:147], v[24:25], 0, s[98:99]
	global_load_dwordx2 v[92:93], v[146:147], off
	v_lshl_add_u64 v[146:147], v[18:19], 0, s[98:99]
	global_load_dwordx2 v[94:95], v[146:147], off
	s_add_u32 s98, s98, 0x10000
	v_lshl_add_u64 v[146:147], v[24:25], 0, s[98:99]
	global_load_dwordx2 v[96:97], v[146:147], off
	v_lshl_add_u64 v[146:147], v[18:19], 0, s[98:99]
	global_load_dwordx2 v[98:99], v[146:147], off
	s_add_u32 s98, s98, 0x10000
	v_lshl_add_u64 v[146:147], v[24:25], 0, s[98:99]
	global_load_dwordx2 v[100:101], v[146:147], off
	v_lshl_add_u64 v[146:147], v[18:19], 0, s[98:99]
	global_load_dwordx2 v[102:103], v[146:147], off
	s_mov_b32 s100, 0xed00000
	s_mov_b32 s101, 0
	ds_read_b128 v[104:107], v26 offset:0
	ds_read_b128 v[108:111], v26 offset:64
	ds_read_b128 v[112:115], v26 offset:128
	ds_read_b128 v[116:119], v26 offset:192
	ds_read_b128 v[120:123], v26 offset:4352
	ds_read_b128 v[124:127], v26 offset:4416
	ds_read_b128 v[128:131], v26 offset:4480
	ds_read_b128 v[132:135], v26 offset:4544
	s_waitcnt lgkmcnt(4)
	v_mfma_f32_16x16x32_bf16 v[136:139], v[2:5], v[104:107], 0
	v_mfma_f32_16x16x32_bf16 v[136:139], v[6:9], v[108:111], v[136:139]
	v_mfma_f32_16x16x32_bf16 v[136:139], v[10:13], v[112:115], v[136:139]
	v_mfma_f32_16x16x32_bf16 v[136:139], v[14:17], v[116:119], v[136:139]
	ds_read_b128 v[104:107], v26 offset:8704
	ds_read_b128 v[108:111], v26 offset:8768
	ds_read_b128 v[112:115], v26 offset:8832
	ds_read_b128 v[116:119], v26 offset:8896
	s_waitcnt vmcnt(0)
	s_waitcnt lgkmcnt(4)
	v_mfma_f32_16x16x32_bf16 v[140:143], v[2:5], v[120:123], 0
	v_mfma_f32_16x16x32_bf16 v[140:143], v[6:9], v[124:127], v[140:143]
	v_mfma_f32_16x16x32_bf16 v[140:143], v[10:13], v[128:131], v[140:143]
	v_mfma_f32_16x16x32_bf16 v[140:143], v[14:17], v[132:135], v[140:143]
	ds_read_b128 v[120:123], v26 offset:13056
	ds_read_b128 v[124:127], v26 offset:13120
	ds_read_b128 v[128:131], v26 offset:13184
	ds_read_b128 v[132:135], v26 offset:13248
	v_add_f32_e32 v148, v136, v80
	v_add_f32_e32 v149, v137, v80
	v_add_f32_e32 v150, v138, v80
	v_add_f32_e32 v151, v139, v80
	v_lshlrev_b32_e32 v152, 16, v88
	v_and_b32_e32 v153, 0xffff0000, v88
	v_lshlrev_b32_e32 v154, 16, v89
	v_and_b32_e32 v155, 0xffff0000, v89
	v_mul_f32_e32 v148, v148, v152
	v_mul_f32_e32 v149, v149, v153
	v_mul_f32_e32 v150, v150, v154
	v_mul_f32_e32 v151, v151, v155
	v_cvt_pk_bf16_f32 v148, v148, v149
	v_cvt_pk_bf16_f32 v149, v150, v151
	v_lshl_add_u64 v[146:147], v[24:25], 0, s[100:101]
	global_store_dwordx2 v[146:147], v[148:149], off offset:1024
	s_waitcnt lgkmcnt(4)
	v_mfma_f32_16x16x32_bf16 v[136:139], v[2:5], v[104:107], 0
	v_mfma_f32_16x16x32_bf16 v[136:139], v[6:9], v[108:111], v[136:139]
	v_mfma_f32_16x16x32_bf16 v[136:139], v[10:13], v[112:115], v[136:139]
	v_mfma_f32_16x16x32_bf16 v[136:139], v[14:17], v[116:119], v[136:139]
	ds_read_b128 v[104:107], v26 offset:17408
	ds_read_b128 v[108:111], v26 offset:17472
	ds_read_b128 v[112:115], v26 offset:17536
	ds_read_b128 v[116:119], v26 offset:17600
	v_add_f32_e32 v148, v140, v81
	v_add_f32_e32 v149, v141, v81
	v_add_f32_e32 v150, v142, v81
	v_add_f32_e32 v151, v143, v81
	v_lshlrev_b32_e32 v152, 16, v90
	v_and_b32_e32 v153, 0xffff0000, v90
	v_lshlrev_b32_e32 v154, 16, v91
	v_and_b32_e32 v155, 0xffff0000, v91
	v_mul_f32_e32 v148, v148, v152
	v_mul_f32_e32 v149, v149, v153
	v_mul_f32_e32 v150, v150, v154
	v_mul_f32_e32 v151, v151, v155
	v_cvt_pk_bf16_f32 v148, v148, v149
	v_cvt_pk_bf16_f32 v149, v150, v151
	v_lshl_add_u64 v[146:147], v[18:19], 0, s[100:101]
	global_store_dwordx2 v[146:147], v[148:149], off offset:1024
	s_add_u32 s100, s100, 0x10000
	s_waitcnt lgkmcnt(4)
	v_mfma_f32_16x16x32_bf16 v[140:143], v[2:5], v[120:123], 0
	v_mfma_f32_16x16x32_bf16 v[140:143], v[6:9], v[124:127], v[140:143]
	v_mfma_f32_16x16x32_bf16 v[140:143], v[10:13], v[128:131], v[140:143]
	v_mfma_f32_16x16x32_bf16 v[140:143], v[14:17], v[132:135], v[140:143]
	ds_read_b128 v[120:123], v26 offset:21760
	ds_read_b128 v[124:127], v26 offset:21824
	ds_read_b128 v[128:131], v26 offset:21888
	ds_read_b128 v[132:135], v26 offset:21952
	v_add_f32_e32 v148, v136, v82
	v_add_f32_e32 v149, v137, v82
	v_add_f32_e32 v150, v138, v82
	v_add_f32_e32 v151, v139, v82
	v_lshlrev_b32_e32 v152, 16, v92
	v_and_b32_e32 v153, 0xffff0000, v92
	v_lshlrev_b32_e32 v154, 16, v93
	v_and_b32_e32 v155, 0xffff0000, v93
	v_mul_f32_e32 v148, v148, v152
	v_mul_f32_e32 v149, v149, v153
	v_mul_f32_e32 v150, v150, v154
	v_mul_f32_e32 v151, v151, v155
	v_cvt_pk_bf16_f32 v148, v148, v149
	v_cvt_pk_bf16_f32 v149, v150, v151
	v_lshl_add_u64 v[146:147], v[24:25], 0, s[100:101]
	global_store_dwordx2 v[146:147], v[148:149], off offset:1024
	s_waitcnt lgkmcnt(4)
	v_mfma_f32_16x16x32_bf16 v[136:139], v[2:5], v[104:107], 0
	v_mfma_f32_16x16x32_bf16 v[136:139], v[6:9], v[108:111], v[136:139]
	v_mfma_f32_16x16x32_bf16 v[136:139], v[10:13], v[112:115], v[136:139]
	v_mfma_f32_16x16x32_bf16 v[136:139], v[14:17], v[116:119], v[136:139]
	ds_read_b128 v[104:107], v26 offset:26112
	ds_read_b128 v[108:111], v26 offset:26176
	ds_read_b128 v[112:115], v26 offset:26240
	ds_read_b128 v[116:119], v26 offset:26304
	v_add_f32_e32 v148, v140, v83
	v_add_f32_e32 v149, v141, v83
	v_add_f32_e32 v150, v142, v83
	v_add_f32_e32 v151, v143, v83
	v_lshlrev_b32_e32 v152, 16, v94
	v_and_b32_e32 v153, 0xffff0000, v94
	v_lshlrev_b32_e32 v154, 16, v95
	v_and_b32_e32 v155, 0xffff0000, v95
	v_mul_f32_e32 v148, v148, v152
	v_mul_f32_e32 v149, v149, v153
	v_mul_f32_e32 v150, v150, v154
	v_mul_f32_e32 v151, v151, v155
	v_cvt_pk_bf16_f32 v148, v148, v149
	v_cvt_pk_bf16_f32 v149, v150, v151
	v_lshl_add_u64 v[146:147], v[18:19], 0, s[100:101]
	global_store_dwordx2 v[146:147], v[148:149], off offset:1024
	s_add_u32 s100, s100, 0x10000
	s_waitcnt lgkmcnt(4)
	v_mfma_f32_16x16x32_bf16 v[140:143], v[2:5], v[120:123], 0
	v_mfma_f32_16x16x32_bf16 v[140:143], v[6:9], v[124:127], v[140:143]
	v_mfma_f32_16x16x32_bf16 v[140:143], v[10:13], v[128:131], v[140:143]
	v_mfma_f32_16x16x32_bf16 v[140:143], v[14:17], v[132:135], v[140:143]
	ds_read_b128 v[120:123], v26 offset:30464
	ds_read_b128 v[124:127], v26 offset:30528
	ds_read_b128 v[128:131], v26 offset:30592
	ds_read_b128 v[132:135], v26 offset:30656
	v_add_f32_e32 v148, v136, v84
	v_add_f32_e32 v149, v137, v84
	v_add_f32_e32 v150, v138, v84
	v_add_f32_e32 v151, v139, v84
	v_lshlrev_b32_e32 v152, 16, v96
	v_and_b32_e32 v153, 0xffff0000, v96
	v_lshlrev_b32_e32 v154, 16, v97
	v_and_b32_e32 v155, 0xffff0000, v97
	v_mul_f32_e32 v148, v148, v152
	v_mul_f32_e32 v149, v149, v153
	v_mul_f32_e32 v150, v150, v154
	v_mul_f32_e32 v151, v151, v155
	v_cvt_pk_bf16_f32 v148, v148, v149
	v_cvt_pk_bf16_f32 v149, v150, v151
	v_lshl_add_u64 v[146:147], v[24:25], 0, s[100:101]
	global_store_dwordx2 v[146:147], v[148:149], off offset:1024
	s_waitcnt lgkmcnt(4)
	v_mfma_f32_16x16x32_bf16 v[136:139], v[2:5], v[104:107], 0
	v_mfma_f32_16x16x32_bf16 v[136:139], v[6:9], v[108:111], v[136:139]
	v_mfma_f32_16x16x32_bf16 v[136:139], v[10:13], v[112:115], v[136:139]
	v_mfma_f32_16x16x32_bf16 v[136:139], v[14:17], v[116:119], v[136:139]
	v_add_f32_e32 v148, v140, v85
	v_add_f32_e32 v149, v141, v85
	v_add_f32_e32 v150, v142, v85
	v_add_f32_e32 v151, v143, v85
	v_lshlrev_b32_e32 v152, 16, v98
	v_and_b32_e32 v153, 0xffff0000, v98
	v_lshlrev_b32_e32 v154, 16, v99
	v_and_b32_e32 v155, 0xffff0000, v99
	v_mul_f32_e32 v148, v148, v152
	v_mul_f32_e32 v149, v149, v153
	v_mul_f32_e32 v150, v150, v154
	v_mul_f32_e32 v151, v151, v155
	v_cvt_pk_bf16_f32 v148, v148, v149
	v_cvt_pk_bf16_f32 v149, v150, v151
	v_lshl_add_u64 v[146:147], v[18:19], 0, s[100:101]
	global_store_dwordx2 v[146:147], v[148:149], off offset:1024
	s_add_u32 s100, s100, 0x10000
	s_waitcnt lgkmcnt(0)
	v_mfma_f32_16x16x32_bf16 v[140:143], v[2:5], v[120:123], 0
	v_mfma_f32_16x16x32_bf16 v[140:143], v[6:9], v[124:127], v[140:143]
	v_mfma_f32_16x16x32_bf16 v[140:143], v[10:13], v[128:131], v[140:143]
	v_mfma_f32_16x16x32_bf16 v[140:143], v[14:17], v[132:135], v[140:143]
	v_add_f32_e32 v148, v136, v86
	v_add_f32_e32 v149, v137, v86
	v_add_f32_e32 v150, v138, v86
	v_add_f32_e32 v151, v139, v86
	v_lshlrev_b32_e32 v152, 16, v100
	v_and_b32_e32 v153, 0xffff0000, v100
	v_lshlrev_b32_e32 v154, 16, v101
	v_and_b32_e32 v155, 0xffff0000, v101
	v_mul_f32_e32 v148, v148, v152
	v_mul_f32_e32 v149, v149, v153
	v_mul_f32_e32 v150, v150, v154
	v_mul_f32_e32 v151, v151, v155
	v_cvt_pk_bf16_f32 v148, v148, v149
	v_cvt_pk_bf16_f32 v149, v150, v151
	v_lshl_add_u64 v[146:147], v[24:25], 0, s[100:101]
	global_store_dwordx2 v[146:147], v[148:149], off offset:1024
	s_nop 7
	s_nop 1
	v_add_f32_e32 v148, v140, v87
	v_add_f32_e32 v149, v141, v87
	v_add_f32_e32 v150, v142, v87
	v_add_f32_e32 v151, v143, v87
	v_lshlrev_b32_e32 v152, 16, v102
	v_and_b32_e32 v153, 0xffff0000, v102
	v_lshlrev_b32_e32 v154, 16, v103
	v_and_b32_e32 v155, 0xffff0000, v103
	v_mul_f32_e32 v148, v148, v152
	v_mul_f32_e32 v149, v149, v153
	v_mul_f32_e32 v150, v150, v154
	v_mul_f32_e32 v151, v151, v155
	v_cvt_pk_bf16_f32 v148, v148, v149
	v_cvt_pk_bf16_f32 v149, v150, v151
	v_lshl_add_u64 v[146:147], v[18:19], 0, s[100:101]
	global_store_dwordx2 v[146:147], v[148:149], off offset:1024
	s_barrier
	s_branch .LBB0_245
